# maximal stack of all validated small changes (S step prefetch+fold, PV early start, P3 prefetch, packed REG2 epilogue, peel, three local barriers)
# speedup vs baseline: 1.0002x; 1.0002x over previous
;     ...
;         for (int j = -1; j < blk; ++j) {
;           {
;             const bf16_t* kp = Mk + (krow0 + (j + 1) * 256 + 64 * sw + prow) * 64 + fq * 8;
.LBB0_654:
	s_add_i32 s16, s19, 1
	s_lshl_b32 s22, s16, 15

;     ...
;             const bf16_t* kp = Mk + (krow0 + (j + 1) * 256 + 64 * sw + prow) * 64 + fq * 8;
	s_ashr_i32 s23, s22, 31
	v_lshl_add_u64 v[2:3], v[112:113], 0, s[22:23]

;     ...
;           const int n = j < 0 ? 0 : (own ? 256 : cnt[j]), ntile = (n + 15) >> 4;
;           for (int s0 = 0; s0 < ntile; s0 += 2, ++stepc) {
;     ...
;             const bf16_t* kp = Mk + (krow0 + (j + 1) * 256 + 64 * sw + prow) * 64 + fq * 8;
; #pragma unroll
;             for (int g = 0; g < 2; ++g)
; #pragma unroll
;               for (int par = 0; par < 2; ++par) { kn[g * 2 + par][0] = *(const bf16x8*)(kp + (32 * g + 4 * par) * 64); kn[g * 2 + par][1] = *(const bf16x8*)(kp + (32 * g + 4 * par) * 64 + 32); }
	global_load_dwordx4 v[30:33], v[2:3], off
	global_load_dwordx4 v[26:29], v[2:3], off offset:1024
	global_load_dwordx4 v[22:25], v[2:3], off offset:2048
	global_load_dwordx4 v[18:21], v[2:3], off offset:3072
	v_add_co_u32_e32 v2, vcc, 0x1000, v2
	s_cmp_lt_i32 s19, 0
	s_nop 0
	v_addc_co_u32_e32 v3, vcc, 0, v3, vcc
	global_load_dwordx4 v[14:17], v[2:3], off
	global_load_dwordx4 v[10:13], v[2:3], off offset:1024
	global_load_dwordx4 v[6:9], v[2:3], off offset:2048
	s_nop 0
	global_load_dwordx4 v[2:5], v[2:3], off offset:3072
	s_mov_b32 s17, 0
	s_cbranch_scc1 .LBB0_656
	s_waitcnt lgkmcnt(0)
	v_readfirstlane_b32 s17, v116
.LBB0_656:
	s_add_i32 s19, s17, 15
	s_ashr_i32 s19, s19, 4
	s_cmp_lt_i32 s19, 1
	s_cbranch_scc1 .LBB0_662
	s_add_i32 s22, s19, -1
	s_lshr_b32 s22, s22, 1
	s_add_i32 s23, s22, 1
	s_mov_b32 s21, 1
	s_mov_b32 s99, 0
	s_add_i32 s22, s23, s15
	s_lshl_b32 s15, s15, 14
	s_mov_b32 s30, s14
	s_branch .LBB0_659

; #define LAS __attribute__((address_space(3)))
; DI unsigned pk2(float lo, float hi) { f32x2 v = {lo, hi}; bf16v2 b = __builtin_convertvector(v, bf16v2); return __builtin_bit_cast(unsigned, b); }
; DI float fast_exp2(float x) { return __builtin_amdgcn_exp2f(x); }
; #define MFMA16(a, b, c) __builtin_amdgcn_mfma_f32_16x16x32_bf16((a), (b), (c), 0, 0, 0)
; #define MO_BARRIER do { asm volatile("s_waitcnt lgkmcnt(0)" ::: "memory"); __builtin_amdgcn_s_barrier(); asm volatile("" ::: "memory"); } while (0)
;     ...
;           for (int s0 = 0; s0 < ntile; s0 += 2, ++stepc) {
;             LAS unsigned char* pbuf = Pb + (stepc & 1) * 16384;
;             if (!(mode & 4))
; #pragma unroll
;             for (int tt = 0; tt < 2; ++tt) {
;               const int tile = s0 + tt;
;               if (tile < ntile) {
;                 const int rem = n - tile * 16;
;                 const int qidx = own ? tile * 16 + fr : (int)list[j * 256 + tile * 16 + (fr < rem ? fr : 0)];
;                 const bf16x8 q0 = *(const LAS bf16x8*)(Qs + qidx * MO_QS + fq * 16), q1 = *(const LAS bf16x8*)(Qs + qidx * MO_QS + 64 + fq * 16);
; #pragma unroll
;                 for (int g = 0; g < 2; ++g) {
;                   f32x4 sv[2];
; #pragma unroll
;                   for (int par = 0; par < 2; ++par) { sv[par] = MFMA16(kf[g * 2 + par][0], q0, ((f32x4){0.f, 0.f, 0.f, 0.f})); sv[par] = MFMA16(kf[g * 2 + par][1], q1, sv[par]); }
;                   float pv[2][4];
; #pragma unroll
;                   for (int par = 0; par < 2; ++par)
; #pragma unroll
;                     for (int i = 0; i < 4; ++i) {
;                       float pe = fast_exp2(sv[par][i] - c2);
;                       if (own) { const int key = 64 * sw + 32 * g + fq * 8 + 4 * par + i; if (key > qidx) pe = 0.f; }
;                       pv[par][i] = pe;
;                     }
;                   u32x4 pw; pw.x = pk2(pv[0][0], pv[0][1]); pw.y = pk2(pv[0][2], pv[0][3]); pw.z = pk2(pv[1][0], pv[1][1]); pw.w = pk2(pv[1][2], pv[1][3]);
;                   *(LAS u32x4*)(pbuf + tt * 8192 + (2 * sw + g) * 1024 + lane * 16) = pw;
;                 }
;               }
;             }
;             MO_BARRIER;
.LBB0_659:
	s_and_b32 s31, s15, 0x4000
	s_cmp_eq_u32 s99, 0
	s_cbranch_scc0 .Lsp_body
	s_add_i32 s98, s17, 0
	v_cmp_gt_i32_e32 vcc, s98, v193
	s_nop 1
	v_cndmask_b32_e32 v1, 0, v193, vcc
	v_add3_u32 v1, s30, v1, -16
	ds_read_u8 v1, v1
	s_add_i32 s98, s17, -16
	v_cmp_gt_i32_e32 vcc, s98, v193
	s_nop 1
	v_cndmask_b32_e32 v91, 0, v193, vcc
	v_add3_u32 v91, s30, v91, 0
	ds_read_u8 v91, v91
	s_waitcnt lgkmcnt(0)
	v_mad_u32_u24 v1, v1, s59, v225
	v_mad_u32_u24 v91, v91, s59, v225
	ds_read_b128 v[92:95], v1
	ds_read_b128 v[96:99], v1 offset:64
	ds_read_b128 v[100:103], v91
	ds_read_b128 v[104:107], v91 offset:64
	s_waitcnt lgkmcnt(0)
.Lsp_body:
	s_cmp_ge_i32 s21, s19
	s_cbranch_scc1 .Lsp_one
	v_mfma_f32_16x16x32_bf16 v[124:127], v[34:37], v[92:95], v[108:111]
	v_mfma_f32_16x16x32_bf16 v[128:131], v[42:45], v[92:95], v[108:111]
	v_mfma_f32_16x16x32_bf16 v[132:135], v[50:53], v[92:95], v[108:111]
	v_mfma_f32_16x16x32_bf16 v[136:139], v[58:61], v[92:95], v[108:111]
	v_mfma_f32_16x16x32_bf16 v[124:127], v[38:41], v[96:99], v[124:127]
	v_mfma_f32_16x16x32_bf16 v[128:131], v[46:49], v[96:99], v[128:131]
	v_mfma_f32_16x16x32_bf16 v[132:135], v[54:57], v[96:99], v[132:135]
	v_mfma_f32_16x16x32_bf16 v[136:139], v[62:65], v[96:99], v[136:139]
	v_mfma_f32_16x16x32_bf16 v[148:151], v[34:37], v[100:103], v[108:111]
	v_mfma_f32_16x16x32_bf16 v[152:155], v[42:45], v[100:103], v[108:111]
	v_mfma_f32_16x16x32_bf16 v[156:159], v[50:53], v[100:103], v[108:111]
	v_mfma_f32_16x16x32_bf16 v[160:163], v[58:61], v[100:103], v[108:111]
	v_mfma_f32_16x16x32_bf16 v[148:151], v[38:41], v[104:107], v[148:151]
	v_mfma_f32_16x16x32_bf16 v[152:155], v[46:49], v[104:107], v[152:155]
	v_mfma_f32_16x16x32_bf16 v[156:159], v[54:57], v[104:107], v[156:159]
	v_mfma_f32_16x16x32_bf16 v[160:163], v[62:65], v[104:107], v[160:163]
	v_add_u32_e32 v1, s31, v226
	s_cmp_gt_u32 s23, 1
	s_cbranch_scc0 .Lsp_last
	s_add_i32 s98, s17, -32
	v_cmp_gt_i32_e32 vcc, s98, v193
	s_nop 1
	v_cndmask_b32_e32 v114, 0, v193, vcc
	v_add3_u32 v114, s30, v114, 16
	ds_read_u8 v114, v114
	s_add_i32 s98, s17, -48
	v_cmp_gt_i32_e32 vcc, s98, v193
	s_nop 1
	v_cndmask_b32_e32 v115, 0, v193, vcc
	v_add3_u32 v115, s30, v115, 32
	ds_read_u8 v115, v115
	v_exp_f32_e32 v124, v124
	v_exp_f32_e32 v125, v125
	v_exp_f32_e32 v126, v126
	v_exp_f32_e32 v127, v127
	v_exp_f32_e32 v128, v128
	v_exp_f32_e32 v129, v129
	v_exp_f32_e32 v130, v130
	v_exp_f32_e32 v131, v131
	v_cvt_pk_bf16_f32 v140, v124, v125
	v_cvt_pk_bf16_f32 v141, v126, v127
	v_cvt_pk_bf16_f32 v142, v128, v129
	v_cvt_pk_bf16_f32 v143, v130, v131
	ds_write_b128 v1, v[140:143]
	v_exp_f32_e32 v132, v132
	v_exp_f32_e32 v133, v133
	v_exp_f32_e32 v134, v134
	v_exp_f32_e32 v135, v135
	v_exp_f32_e32 v136, v136
	v_exp_f32_e32 v137, v137
	v_exp_f32_e32 v138, v138
	v_exp_f32_e32 v139, v139
	v_cvt_pk_bf16_f32 v144, v132, v133
	v_cvt_pk_bf16_f32 v145, v134, v135
	v_cvt_pk_bf16_f32 v146, v136, v137
	v_cvt_pk_bf16_f32 v147, v138, v139
	ds_write_b128 v1, v[144:147] offset:1024
	s_waitcnt lgkmcnt(2)
	v_mad_u32_u24 v114, v114, s59, v225
	v_mad_u32_u24 v115, v115, s59, v225
	ds_read_b128 v[92:95], v114
	ds_read_b128 v[96:99], v114 offset:64
	ds_read_b128 v[100:103], v115
	ds_read_b128 v[104:107], v115 offset:64
	v_exp_f32_e32 v148, v148
	v_exp_f32_e32 v149, v149
	v_exp_f32_e32 v150, v150
	v_exp_f32_e32 v151, v151
	v_exp_f32_e32 v152, v152
	v_exp_f32_e32 v153, v153
	v_exp_f32_e32 v154, v154
	v_exp_f32_e32 v155, v155
	v_cvt_pk_bf16_f32 v164, v148, v149
	v_cvt_pk_bf16_f32 v165, v150, v151
	v_cvt_pk_bf16_f32 v166, v152, v153
	v_cvt_pk_bf16_f32 v167, v154, v155
	ds_write_b128 v1, v[164:167] offset:8192
	v_exp_f32_e32 v156, v156
	v_exp_f32_e32 v157, v157
	v_exp_f32_e32 v158, v158
	v_exp_f32_e32 v159, v159
	v_exp_f32_e32 v160, v160
	v_exp_f32_e32 v161, v161
	v_exp_f32_e32 v162, v162
	v_exp_f32_e32 v163, v163
	v_cvt_pk_bf16_f32 v168, v156, v157
	v_cvt_pk_bf16_f32 v169, v158, v159
	v_cvt_pk_bf16_f32 v170, v160, v161
	v_cvt_pk_bf16_f32 v171, v162, v163
	ds_write_b128 v1, v[168:171] offset:9216
	s_mov_b32 s99, 1
	s_branch .LBB0_658
; #define LAS __attribute__((address_space(3)))
; DI unsigned pk2(float lo, float hi) { f32x2 v = {lo, hi}; bf16v2 b = __builtin_convertvector(v, bf16v2); return __builtin_bit_cast(unsigned, b); }
; DI float fast_exp2(float x) { return __builtin_amdgcn_exp2f(x); }
; #define MFMA16(a, b, c) __builtin_amdgcn_mfma_f32_16x16x32_bf16((a), (b), (c), 0, 0, 0)
;     ...
;             for (int tt = 0; tt < 2; ++tt) {
;               const int tile = s0 + tt;
;               if (tile < ntile) {
;                 const int rem = n - tile * 16;
;                 const int qidx = own ? tile * 16 + fr : (int)list[j * 256 + tile * 16 + (fr < rem ? fr : 0)];
;                 const bf16x8 q0 = *(const LAS bf16x8*)(Qs + qidx * MO_QS + fq * 16), q1 = *(const LAS bf16x8*)(Qs + qidx * MO_QS + 64 + fq * 16);
; #pragma unroll
;                 for (int g = 0; g < 2; ++g) {
;                   f32x4 sv[2];
; #pragma unroll
;                   for (int par = 0; par < 2; ++par) { sv[par] = MFMA16(kf[g * 2 + par][0], q0, ((f32x4){0.f, 0.f, 0.f, 0.f})); sv[par] = MFMA16(kf[g * 2 + par][1], q1, sv[par]); }
;                   float pv[2][4];
; #pragma unroll
;                   for (int par = 0; par < 2; ++par)
; #pragma unroll
;                     for (int i = 0; i < 4; ++i) {
;                       float pe = fast_exp2(sv[par][i] - c2);
;                       if (own) { const int key = 64 * sw + 32 * g + fq * 8 + 4 * par + i; if (key > qidx) pe = 0.f; }
;                       pv[par][i] = pe;
;                     }
;                   u32x4 pw; pw.x = pk2(pv[0][0], pv[0][1]); pw.y = pk2(pv[0][2], pv[0][3]); pw.z = pk2(pv[1][0], pv[1][1]); pw.w = pk2(pv[1][2], pv[1][3]);
;                   *(LAS u32x4*)(pbuf + tt * 8192 + (2 * sw + g) * 1024 + lane * 16) = pw;
;                 }
;               }
;             }
.Lsp_last:
	s_nop 7
	v_exp_f32_e32 v124, v124
	v_exp_f32_e32 v125, v125
	v_exp_f32_e32 v126, v126
	v_exp_f32_e32 v127, v127
	v_exp_f32_e32 v128, v128
	v_exp_f32_e32 v129, v129
	v_exp_f32_e32 v130, v130
	v_exp_f32_e32 v131, v131
	v_cvt_pk_bf16_f32 v140, v124, v125
	v_cvt_pk_bf16_f32 v141, v126, v127
	v_cvt_pk_bf16_f32 v142, v128, v129
	v_cvt_pk_bf16_f32 v143, v130, v131
	ds_write_b128 v1, v[140:143]
	v_exp_f32_e32 v132, v132
	v_exp_f32_e32 v133, v133
	v_exp_f32_e32 v134, v134
	v_exp_f32_e32 v135, v135
	v_exp_f32_e32 v136, v136
	v_exp_f32_e32 v137, v137
	v_exp_f32_e32 v138, v138
	v_exp_f32_e32 v139, v139
	v_cvt_pk_bf16_f32 v144, v132, v133
	v_cvt_pk_bf16_f32 v145, v134, v135
	v_cvt_pk_bf16_f32 v146, v136, v137
	v_cvt_pk_bf16_f32 v147, v138, v139
	ds_write_b128 v1, v[144:147] offset:1024
	v_exp_f32_e32 v148, v148
	v_exp_f32_e32 v149, v149
	v_exp_f32_e32 v150, v150
	v_exp_f32_e32 v151, v151
	v_exp_f32_e32 v152, v152
	v_exp_f32_e32 v153, v153
	v_exp_f32_e32 v154, v154
	v_exp_f32_e32 v155, v155
	v_cvt_pk_bf16_f32 v164, v148, v149
	v_cvt_pk_bf16_f32 v165, v150, v151
	v_cvt_pk_bf16_f32 v166, v152, v153
	v_cvt_pk_bf16_f32 v167, v154, v155
	ds_write_b128 v1, v[164:167] offset:8192
	v_exp_f32_e32 v156, v156
	v_exp_f32_e32 v157, v157
	v_exp_f32_e32 v158, v158
	v_exp_f32_e32 v159, v159
	v_exp_f32_e32 v160, v160
	v_exp_f32_e32 v161, v161
	v_exp_f32_e32 v162, v162
	v_exp_f32_e32 v163, v163
	v_cvt_pk_bf16_f32 v168, v156, v157
	v_cvt_pk_bf16_f32 v169, v158, v159
	v_cvt_pk_bf16_f32 v170, v160, v161
	v_cvt_pk_bf16_f32 v171, v162, v163
	ds_write_b128 v1, v[168:171] offset:9216
	s_mov_b32 s99, 0
	s_branch .LBB0_658
.Lsp_one:
	v_mfma_f32_16x16x32_bf16 v[124:127], v[34:37], v[92:95], v[108:111]
	v_mfma_f32_16x16x32_bf16 v[128:131], v[42:45], v[92:95], v[108:111]
	v_mfma_f32_16x16x32_bf16 v[132:135], v[50:53], v[92:95], v[108:111]
	v_mfma_f32_16x16x32_bf16 v[136:139], v[58:61], v[92:95], v[108:111]
	v_mfma_f32_16x16x32_bf16 v[124:127], v[38:41], v[96:99], v[124:127]
	v_mfma_f32_16x16x32_bf16 v[128:131], v[46:49], v[96:99], v[128:131]
	v_mfma_f32_16x16x32_bf16 v[132:135], v[54:57], v[96:99], v[132:135]
	v_mfma_f32_16x16x32_bf16 v[136:139], v[62:65], v[96:99], v[136:139]
	v_add_u32_e32 v1, s31, v226
	s_nop 7
	v_exp_f32_e32 v124, v124
	v_exp_f32_e32 v125, v125
	v_exp_f32_e32 v126, v126
	v_exp_f32_e32 v127, v127
	v_exp_f32_e32 v128, v128
	v_exp_f32_e32 v129, v129
	v_exp_f32_e32 v130, v130
	v_exp_f32_e32 v131, v131
	v_cvt_pk_bf16_f32 v140, v124, v125
	v_cvt_pk_bf16_f32 v141, v126, v127
	v_cvt_pk_bf16_f32 v142, v128, v129
	v_cvt_pk_bf16_f32 v143, v130, v131
	ds_write_b128 v1, v[140:143]
	v_exp_f32_e32 v132, v132
	v_exp_f32_e32 v133, v133
	v_exp_f32_e32 v134, v134
	v_exp_f32_e32 v135, v135
	v_exp_f32_e32 v136, v136
	v_exp_f32_e32 v137, v137
	v_exp_f32_e32 v138, v138
	v_exp_f32_e32 v139, v139
	v_cvt_pk_bf16_f32 v144, v132, v133
	v_cvt_pk_bf16_f32 v145, v134, v135
	v_cvt_pk_bf16_f32 v146, v136, v137
	v_cvt_pk_bf16_f32 v147, v138, v139
	ds_write_b128 v1, v[144:147] offset:1024
	s_mov_b32 s99, 0
	s_branch .LBB0_658

;     ...
;         for (int j = -1; j < blk; ++j) {
;           {
;             const bf16_t* kp = Mk + (krow0 + (j + 1) * 256 + 64 * sw + prow) * 64 + fq * 8;
; #pragma unroll
;             for (int g = 0; g < 2; ++g)
; #pragma unroll
;               for (int par = 0; par < 2; ++par) { kn[g * 2 + par][0] = *(const bf16x8*)(kp + (32 * g + 4 * par) * 64); kn[g * 2 + par][1] = *(const bf16x8*)(kp + (32 * g + 4 * par) * 64 + 32); }
;           }
;           ssteps(j, std::false_type{});
; #pragma unroll
;           for (int a = 0; a < 4; ++a) { kf[a][0] = kn[a][0]; kf[a][1] = kn[a][1]; }
;         }
.LBB0_662:
	s_addk_i32 s14, 0x100
	s_cmp_eq_u32 s16, s18
	s_cbranch_scc1 .LBB0_665
	s_mov_b32 s19, s16
	s_lshl_b32 s98, s16, 2
	s_add_i32 s98, s98, 0x10400
	v_mov_b32_e32 v116, s98
	ds_read_b32 v116, v116
	s_waitcnt vmcnt(7)
	v_pk_mov_b32 v[34:35], v[30:31], v[30:31] op_sel:[0,1]
	v_pk_mov_b32 v[36:37], v[32:33], v[32:33] op_sel:[0,1]
	s_waitcnt vmcnt(6)
	v_pk_mov_b32 v[38:39], v[26:27], v[26:27] op_sel:[0,1]
	v_pk_mov_b32 v[40:41], v[28:29], v[28:29] op_sel:[0,1]
	s_waitcnt vmcnt(5)
	v_pk_mov_b32 v[42:43], v[22:23], v[22:23] op_sel:[0,1]
	v_pk_mov_b32 v[44:45], v[24:25], v[24:25] op_sel:[0,1]
	s_waitcnt vmcnt(4)
	v_pk_mov_b32 v[46:47], v[18:19], v[18:19] op_sel:[0,1]
	v_pk_mov_b32 v[48:49], v[20:21], v[20:21] op_sel:[0,1]
	s_waitcnt vmcnt(3)
	v_pk_mov_b32 v[50:51], v[14:15], v[14:15] op_sel:[0,1]
	v_pk_mov_b32 v[52:53], v[16:17], v[16:17] op_sel:[0,1]
	s_waitcnt vmcnt(2)
	v_pk_mov_b32 v[54:55], v[10:11], v[10:11] op_sel:[0,1]
	v_pk_mov_b32 v[56:57], v[12:13], v[12:13] op_sel:[0,1]
	s_waitcnt vmcnt(1)
	v_pk_mov_b32 v[58:59], v[6:7], v[6:7] op_sel:[0,1]
	v_pk_mov_b32 v[60:61], v[8:9], v[8:9] op_sel:[0,1]
	s_waitcnt vmcnt(0)
	v_pk_mov_b32 v[62:63], v[2:3], v[2:3] op_sel:[0,1]
	v_pk_mov_b32 v[64:65], v[4:5], v[4:5] op_sel:[0,1]
	s_branch .LBB0_654

; #define LAS __attribute__((address_space(3)))
; #define RO_BARRIER do { asm volatile("s_waitcnt lgkmcnt(0)" ::: "memory"); __builtin_amdgcn_s_barrier(); asm volatile("" ::: "memory"); } while (0)
;   const bool dry = mode != 0;
;   unsigned char* ws = p.ws;
;   int tid_ = threadIdx.x; asm volatile("" : "+v"(tid_)); const int tid = tid_, wid = __builtin_amdgcn_readfirstlane(tid >> 6), lane = tid & 63, fr = lane & 15, fq = lane >> 4;
;   const bf16_t* Qr = (const bf16_t*)(ws + OFF_QR); const bf16_t* Kr = (const bf16_t*)(ws + OFF_KR); const bf16_t* Vrt = (const bf16_t*)(ws + OFF_VRT);
;   const bf16_t* RT = (const bf16_t*)p.out;
;   bf16_t* G = (bf16_t*)(ws + OFF_G);
;     ...
;   for (int u = blockIdx.x; u < 1024; u += gridDim.x) {
;     const int bh = u >> 6, c = u & 63, h = bh & 3, b = bh >> 2;
;     const float gam = exp2f(lg2gamma(h));
;     {
;       const u32x4* qg = (const u32x4*)(Qr + (long)(bh * 64 + c) * 16384); const u32x4* kg = (const u32x4*)(Kr + (long)(bh * 64 + c) * 16384);
;       u32x4 qv[4], kv[4];
; #pragma unroll
;       for (int i = 0; i < 4; ++i) { qv[i] = qg[tid + i * NTHREADS]; kv[i] = kg[tid + i * NTHREADS]; }
; #pragma unroll
;       for (int i = 0; i < 4; ++i) { *(LAS u32x4*)(shm + RO_Q + (tid + i * NTHREADS) * 16) = qv[i]; *(LAS u32x4*)(shm + RO_K + (tid + i * NTHREADS) * 16) = kv[i]; }
;     }
;     bf16x8 rf[2][4], vf[2][4];
;     {
;       const bf16_t* rp = RT + (long)(bh * 64 + c) * 32768 + (2 * wid) * 2048 + lane * 8;
;       const bf16_t* vp = Vrt + (long)(bh * 64 + c) * 32768 + (2 * wid) * 2048 + lane * 8;
; #pragma unroll
;       for (int e2 = 0; e2 < 2; ++e2)
; #pragma unroll
;         for (int ks = 0; ks < 4; ++ks) { rf[e2][ks] = *(const bf16x8*)(rp + e2 * 2048 + ks * 512); vf[e2][ks] = *(const bf16x8*)(vp + e2 * 2048 + ks * 512); }
;     }
;     RO_BARRIER;
;     {
;       const int ns2 = (16 * wid + 15) / 32 + 1, n = 16 * wid + fr;
;       bf16x8 qb[4];
; #pragma unroll
;       for (int ks = 0; ks < 4; ++ks) qb[ks] = *(const LAS bf16x8*)(shm + RO_Q + (wid * 4 + ks) * 1024 + lane * 16);
;       for (int s2 = 0; s2 < ns2; ++s2) {
.LBB0_726:
	s_or_b64 exec, exec, s[6:7]
	s_and_saveexec_b64 s[98:99], s[94:95]
	v_add_u32_e32 v248, -1, v240
	v_and_b32_e32 v248, v248, v240
	v_add_u32_e32 v249, -1, v241
	v_and_b32_e32 v249, v249, v241
	v_or_b32_e32 v248, v248, v249
	v_add_u32_e32 v249, -1, v242
	v_and_b32_e32 v249, v249, v242
	v_or_b32_e32 v248, v248, v249
	v_add_u32_e32 v249, -1, v243
	v_and_b32_e32 v249, v249, v243
	v_or_b32_e32 v248, v248, v249
	v_add_u32_e32 v249, -1, v244
	v_and_b32_e32 v249, v249, v244
	v_or_b32_e32 v248, v248, v249
	v_add_u32_e32 v249, -1, v245
	v_and_b32_e32 v249, v249, v245
	v_or_b32_e32 v248, v248, v249
	v_add_u32_e32 v249, -1, v246
	v_and_b32_e32 v249, v249, v246
	v_or_b32_e32 v248, v248, v249
	v_add_u32_e32 v249, -1, v247
	v_and_b32_e32 v249, v249, v247
	v_or_b32_e32 v248, v248, v249
	v_cmp_eq_u32_e32 vcc, 0, v248
	s_nop 1
	v_cndmask_b32_e64 v249, 0, 1, vcc
	v_mov_b32_e32 v253, 0x23ff8
	ds_write_b32 v253, v249
	s_or_b64 exec, exec, s[98:99]
	s_add_u32 s22, s26, 0x2300000
	s_addc_u32 s23, s27, 0
	s_waitcnt vmcnt(27) lgkmcnt(0)
	v_mov_b32_e32 v0, v194
	s_add_u32 s68, s26, 0xc300000
	s_barrier
	s_addc_u32 s69, s27, 0
	s_andn2_b64 vcc, exec, s[0:1]
	v_readfirstlane_b32 s0, v0
	s_cbranch_vccnz .LBB0_755
	s_ashr_i32 s12, s0, 6
	s_lshl_b32 s10, s12, 12
	s_ashr_i32 s11, s10, 31
	s_add_i32 s1, 0, 0x18000
	s_lshl_b64 s[6:7], s[10:11], 1
	s_add_u32 s8, s24, s6
	s_addc_u32 s9, s25, s7
	v_and_b32_e32 v1, 63, v0
	s_waitcnt vmcnt(14)
	v_mov_b32_e32 v91, 0
	s_add_u32 s6, s3, s6
	v_lshlrev_b32_e32 v88, 4, v1
	v_mov_b32_e32 v89, v91
	s_addc_u32 s7, s66, s7
	s_lshl_b32 s3, s12, 4
	s_ashr_i32 s0, s0, 31
	s_waitcnt vmcnt(12)
	v_lshl_add_u64 v[94:95], s[6:7], 0, v[88:89]
	s_or_b32 s6, s3, 15
	s_lshr_b32 s0, s0, 27
	v_and_b32_e32 v3, 15, v0
	s_add_i32 s0, s6, s0
	v_lshl_add_u64 v[92:93], s[8:9], 0, v[88:89]
	s_ashr_i32 s39, s0, 5
	v_or_b32_e32 v89, s3, v3
	s_add_i32 s3, s10, 0
	s_cmpk_gt_i32 s6, 0xffe0
	s_movk_i32 s0, 0x80
	s_cselect_b64 s[40:41], -1, 0
	v_cmp_gt_u32_e64 s[6:7], 16, v1
	v_cmp_gt_i32_e64 s[8:9], s0, v0
	v_lshlrev_b32_e32 v1, 3, v0
	s_add_i32 s11, 0, 0x1a000
	s_mul_i32 s0, s12, 0x2800
	s_waitcnt vmcnt(6)
	v_add_u32_e32 v121, s1, v1
	v_add_u32_e32 v122, s11, v1
	s_add_i32 s13, s0, 0
	v_and_b32_e32 v4, 24, v1
	v_and_b32_e32 v1, 3, v0
	v_lshrrev_b32_e32 v2, 1, v0
	v_lshl_add_u32 v13, v1, 4, s13
	v_lshlrev_b32_e32 v6, 3, v1
	v_ashrrev_i32_e32 v1, 31, v0
	v_lshlrev_b32_e32 v7, 4, v0
	v_and_b32_e32 v9, 24, v2
	v_lshlrev_b32_e32 v2, 8, v0
	v_bfe_u32 v10, v0, 2, 4
	v_lshlrev_b64 v[0:1], 4, v[0:1]
	v_lshlrev_b32_e32 v5, 3, v3
	s_lshl_b32 s30, s12, 10
	v_add_u32_e32 v11, s13, v9
	s_lshl_b32 s0, s12, 5
	v_lshl_add_u64 v[96:97], s[22:23], 0, v[0:1]
	v_lshl_add_u64 v[0:1], s[26:27], 0, v[0:1]
	s_mov_b64 s[12:13], 0x4300000
	v_add_u32_e32 v131, 0, v88
	v_add_u32_e32 v120, s1, v5
	v_add_u32_e32 v123, s11, v5
	v_lshlrev_b32_e32 v8, 10, v10
	v_or_b32_e32 v5, 16, v10
	v_lshl_add_u64 v[98:99], v[0:1], 0, s[12:13]
	v_add_u32_e32 v0, s10, v131
	s_ashr_i32 s1, s0, 31
	v_and_b32_e32 v2, 0x3c00, v2
	v_mul_u32_u24_e32 v15, 0x50, v10
	v_mul_u32_u24_e32 v3, 0x50, v3
	v_mul_u32_u24_e32 v17, 0x50, v5
	v_lshlrev_b32_e32 v10, 10, v5
	v_or_b32_e32 v12, 0x8000, v8
	v_or_b32_e32 v14, 0xc000, v8
	v_or_b32_e32 v16, 0x10000, v8
	v_or_b32_e32 v18, 0x14000, v8
	v_or_b32_e32 v20, 0x18000, v8
	v_or_b32_e32 v22, 0x1c000, v8
	v_add_u32_e32 v132, 0x10000, v0
	v_mbcnt_lo_u32_b32 v0, -1, 0
	s_mov_b32 s18, 0
	s_mov_b32 s19, 0x18000
	s_waitcnt vmcnt(4)
	v_add_u32_e32 v124, 0x80, v123
	v_add_u32_e32 v125, 0x100, v123
	v_add_u32_e32 v126, 0x180, v123
	v_add_u32_e32 v127, 0x200, v123
	v_add_u32_e32 v128, 0x280, v123
	v_add_u32_e32 v129, 0x300, v123
	v_add_u32_e32 v130, 0x380, v123
	s_mov_b32 s31, 0x8000
	s_mov_b32 s38, 0x10000
	s_add_i32 s39, s39, 1
	v_or_b32_e32 v133, 7, v9
	v_add_u32_e32 v134, 0x8000, v131
	v_add_u32_e32 v135, 0, v7
	s_movk_i32 s43, 0x1000
	v_mbcnt_hi_u32_b32 v136, -1, v0
	s_mov_b32 s42, 0x3b800000
	v_add_u32_e32 v137, v11, v3
	s_lshl_b64 s[44:45], s[0:1], 1
	v_lshlrev_b32_e32 v90, 1, v4
	v_lshlrev_b32_e32 v100, 1, v2
	s_mov_b32 s48, 0x20000
	s_mov_b32 s49, 0x28000
	s_mov_b32 s50, 0x30000
	s_mov_b32 s51, 0x38000
	v_lshlrev_b32_e32 v102, 1, v6
	v_add_u32_e32 v138, v13, v15
	v_lshlrev_b32_e32 v104, 1, v8
	v_add_u32_e32 v139, v13, v17
	v_lshlrev_b32_e32 v106, 1, v10
	v_lshlrev_b32_e32 v108, 1, v12
	v_lshlrev_b32_e32 v110, 1, v14
	v_lshlrev_b32_e32 v112, 1, v16
	v_lshlrev_b32_e32 v114, 1, v18
	v_lshlrev_b32_e32 v116, 1, v20
	v_lshlrev_b32_e32 v118, 1, v22
	v_mov_b32_e32 v140, 0x3f7f0000
	v_mov_b32_e32 v141, 0x3f7e0000
	s_mov_b32 s46, s2
	s_mov_b32 s99, 0
	s_mov_b32 s100, 0x2000
	s_mov_b32 s101, 0
	s_branch .LBB0_729
